# fox unit prologue de-serialisation: norm-bound, decay-base and query-row decay loads issued with the Q loads instead of three later dependent round trips (on top of rotary pair reuse and early claim)
# baseline (speedup 1.0000x reference)
; #define LAS __attribute__((address_space(3)))
; template <bool DIFF>
; __device__ __forceinline__ void attn_unit(const AttnP& A, int b, int h, int qi, ldsp lds) {
;     ...
;     const int tid = tid_, lane = tid & 63, w = __builtin_amdgcn_readfirstlane(tid >> 6), r32 = lane & 31, hi = lane >> 5;
;     const int comp = DIFF ? (w >> 2) : 0, wq = DIFF ? (w & 3) : w;
;     const int qstart = qi == 0 ? 0 : 64 + QROWS * (qi - 1);
;     const int nt = qi == 0 ? 1 : 1 + TPQ * qi;
;     const int diag0 = qi == 0 ? 0 : nt - TPQ;
;     const int q_pp = qstart + 32 * wq + r32, qmax_w = qstart + 32 * wq + 31;
;     const bool store_ok = (qi != 0) || (b == 0 && q_pp >= 48 && q_pp < 64);
;     const size_t Rb = (size_t)b * LP;
;     const int qcol = DIFF ? h * 128 + comp * 64 : 2048 + h * 64;
;     const int kcol = DIFF ? 512 + h * 128 : 2560 + h * 64;
;     const int vcol = DIFF ? 1024 + h * 128 : 3072 + h * 64;
;     const int zcol = DIFF ? 1536 + h * 128 : 3584 + h * 64;
;     const int mcol = DIFF ? h * 128 : 512 + h * 64;
;     const bf16* Pq = A.P + (Rb + q_pp) * NP;
;     bf16x8 qf[4];
; #pragma unroll
;     for (int c = 0; c < 4; ++c) qf[c] = *(const bf16x8*)(Pq + qcol + 16 * c + 8 * hi);
;     LAS float* pref = (LAS float*)(lds + LDS_PREF);
;     u32x4 kreg[NPIECE], vreg[NPIECE]; float clreg = 0.f;
;     ...
;     int kt0 = 0;
;     if (!DIFF) {
;         LAS int* kst = (LAS int*)(lds + LDS_MISC + 64);
;         if (tid == 0) *kst = nt - 1;
;         if (w == 0) {
;             float carry = 0.f;
; #pragma unroll
;             for (int ch = 0; ch < 3; ++ch) {
;                 const int idx = ch * 64 + lane;
;                 const float v = idx < TPB ? A.cumtot[(b * TPB + idx) * 8 + h] : 0.f;
;                 float inc = v;
; #pragma unroll
;                 for (int o = 1; o < 64; o <<= 1) { const float t_ = __shfl_up(inc, o); if (lane >= o) inc += t_; }
;                 if (idx < TPB) pref[idx] = carry + inc - v;
;                 if (idx == TPB - 1) pref[TPB] = carry + inc;
;                 carry += __shfl(inc, 63);
;             }
;         }
;         __syncthreads();
.LBB0_445:
	s_or_b64 exec, exec, s[0:1]
	v_mov_b32_e32 v0, s80
	s_waitcnt lgkmcnt(0)
	s_barrier
	ds_read_b32 v0, v0
	s_movk_i32 s0, 0x417
	s_waitcnt lgkmcnt(0)
	s_barrier
	v_cmp_lt_i32_e32 vcc, s0, v0
	v_readfirstlane_b32 s16, v0
	s_mov_b64 s[0:1], -1
	s_cbranch_vccnz .LBB0_440
	s_mul_i32 s0, s30, 0x418
	s_add_i32 s0, s16, s0
	s_ashr_i32 s1, s0, 31
	s_lshl_b64 s[0:1], s[0:1], 2
	s_add_u32 s0, s56, s0
	s_addc_u32 s1, s57, s1
	global_load_dword v0, v1, s[0:1]
	s_movk_i32 s0, 0x207
	s_waitcnt vmcnt(0)
	v_cmp_lt_i32_e32 vcc, s0, v0
	v_readfirstlane_b32 s31, v0
	s_mov_b64 s[0:1], -1
	s_cbranch_vccz .LBB0_495
	s_add_i32 s90, s31, 0xfffffdf8
	s_mul_hi_u32 s0, s90, 0x3e0f83e1
	s_lshr_b32 s1, s0, 3
	s_mul_i32 s1, s1, 33
	s_sub_i32 s25, s90, s1
	s_lshr_b32 s24, s0, 6
	s_bfe_u32 s41, s0, 0x30003
	s_cmp_eq_u32 s25, 0
	s_cselect_b64 s[70:71], -1, 0
	s_lshl_b32 s0, s25, 8
	s_add_i32 s22, s0, 0xffffff40
	s_cmp_lg_u32 s25, 0
	v_mov_b32_e32 v148, v200
	s_cselect_b64 s[16:17], -1, 0
	s_and_b64 s[0:1], s[16:17], exec
	v_readfirstlane_b32 s23, v148
	s_cselect_b32 s22, s22, 0
	s_ashr_i32 s0, s23, 1
	s_and_b32 s40, s0, 0xffffffe0
	v_and_b32_e32 v10, 31, v148
	s_add_i32 s40, s40, s22
	v_or_b32_e32 v146, s40, v10
	v_ashrrev_i32_e32 v147, 31, v146
	v_mad_u64_u32 v[2:3], s[0:1], s24, v221, v[146:147]
	v_lshlrev_b64 v[4:5], 13, v[2:3]
	v_bfe_u32 v12, v148, 5, 1
	v_lshl_add_u64 v[4:5], s[58:59], 0, v[4:5]
	s_lshl_b32 s34, s41, 7
	v_lshl_add_u64 v[144:145], v[4:5], 0, s[34:35]
	v_lshlrev_b32_e32 v150, 4, v12
	v_mov_b32_e32 v151, v1
	v_lshl_add_u64 v[4:5], v[144:145], 0, v[150:151]
	s_mov_b64 s[0:1], 0x1000
	v_lshl_add_u64 v[6:7], v[4:5], 0, s[0:1]
	v_add_co_u32_e32 v4, vcc, 0x1000, v4
	s_lshl_b32 s91, s25, 2
	s_nop 0
	v_addc_co_u32_e32 v5, vcc, 0, v5, vcc
	global_load_dwordx4 v[82:85], v[6:7], off offset:32
	global_load_dwordx4 v[86:89], v[6:7], off offset:64
	global_load_dwordx4 v[90:93], v[4:5], off
	global_load_dwordx4 v[94:97], v[6:7], off offset:96
	s_lshl_b32 s0, s41, 3
	v_mov_b32_e32 v126, s0
	global_load_dwordx2 v[116:117], v126, s[62:63] offset:512
	global_load_dwordx2 v[118:119], v126, s[62:63] offset:576
	s_lshl_b32 s0, s41, 4
	v_mov_b32_e32 v127, s0
	global_load_dwordx4 v[120:123], v127, s[62:63] offset:640
	s_mul_i32 s0, s24, 0x408
	s_or_b32 s0, s0, s41
	s_add_i32 s0, s0, 0x400
	s_mov_b32 s1, 0
	s_lshl_b64 s[0:1], s[0:1], 2
	s_add_u32 s0, s52, s0
	s_addc_u32 s1, s53, s1
	global_load_dword v124, v1, s[0:1]
	v_lshlrev_b64 v[126:127], 5, v[2:3]
	v_lshl_add_u64 v[126:127], s[54:55], 0, v[126:127]
	s_lshl_b32 s0, s41, 2
	s_mov_b32 s1, 0
	v_lshl_add_u64 v[126:127], v[126:127], 0, s[0:1]
	global_load_dword v125, v[126:127], off
	v_cmp_eq_u32_e32 vcc, 0, v148
	s_and_saveexec_b64 s[0:1], vcc
	v_mov_b32_e32 v0, s81
	v_mov_b32_e32 v4, s91
	ds_write_b32 v0, v4
	s_or_b64 exec, exec, s[0:1]
	v_and_b32_e32 v11, 63, v148
	s_mov_b32 s25, s35
	s_cmp_gt_u32 s23, 63
	v_cmp_gt_u32_e32 vcc, 32, v11
	s_cbranch_scc1 .LBB0_453
	s_mul_i32 s0, s24, 0x81
	v_add_u32_e32 v0, s0, v11
	v_lshl_or_b32 v0, v0, 3, s41
	v_lshl_add_u64 v[4:5], v[0:1], 2, s[52:53]
	v_or_b32_e32 v7, 64, v11
	global_load_dword v6, v[4:5], off
	v_add_u32_e32 v0, s0, v7
	v_lshl_or_b32 v0, v0, 3, s41
	v_lshl_add_u64 v[4:5], v[0:1], 2, s[52:53]
	global_load_dword v5, v[4:5], off
	v_cmp_lt_i32_e64 s[44:45], v214, v209
	v_add_u32_e32 v0, -1, v208
	v_add_u32_e32 v4, -2, v208
	v_cndmask_b32_e64 v9, v214, v208, s[44:45]
	v_cmp_lt_i32_e64 s[44:45], v215, v209
	v_add_u32_e32 v8, -4, v208
	v_cmp_gt_u32_e64 s[46:47], 2, v11
	v_cndmask_b32_e64 v13, v215, v208, s[44:45]
	v_cmp_lt_i32_e64 s[44:45], v216, v209
	v_lshlrev_b32_e32 v9, 2, v9
	v_lshlrev_b32_e32 v13, 2, v13
	v_cndmask_b32_e64 v14, v216, v208, s[44:45]
	v_cmp_lt_i32_e64 s[44:45], v0, v209
	s_nop 1
	v_cndmask_b32_e64 v0, v0, v208, s[44:45]
	v_lshlrev_b32_e32 v0, 2, v0
	v_cmp_lt_i32_e64 s[44:45], v4, v209
	s_waitcnt vmcnt(1)
	ds_bpermute_b32 v15, v0, v6
	v_cndmask_b32_e64 v4, v4, v208, s[44:45]
	v_cmp_lt_i32_e64 s[44:45], v8, v209
	v_lshlrev_b32_e32 v4, 2, v4
	s_waitcnt vmcnt(0)
	ds_bpermute_b32 v0, v0, v5
	v_cndmask_b32_e64 v8, v8, v208, s[44:45]
	s_waitcnt lgkmcnt(1)
	v_add_f32_e32 v15, v6, v15
	v_cmp_eq_u32_e64 s[44:45], 0, v11
	v_lshlrev_b32_e32 v8, 2, v8
	s_waitcnt lgkmcnt(0)
	v_add_f32_e32 v0, v5, v0
	v_cndmask_b32_e64 v15, v15, v6, s[44:45]
	ds_bpermute_b32 v16, v4, v15
	v_cndmask_b32_e64 v0, v0, v5, s[44:45]
	ds_bpermute_b32 v4, v4, v0
	s_waitcnt lgkmcnt(1)
	v_add_f32_e32 v16, v15, v16
	v_cndmask_b32_e64 v15, v16, v15, s[46:47]
	ds_bpermute_b32 v16, v8, v15
	s_waitcnt lgkmcnt(1)
	v_add_f32_e32 v4, v0, v4
	v_cndmask_b32_e64 v0, v4, v0, s[46:47]
	ds_bpermute_b32 v4, v8, v0
	v_cmp_gt_u32_e64 s[46:47], 4, v11
	s_waitcnt lgkmcnt(1)
	v_add_f32_e32 v8, v15, v16
	s_waitcnt lgkmcnt(0)
	v_add_f32_e32 v4, v0, v4
	v_cndmask_b32_e64 v8, v8, v15, s[46:47]
	ds_bpermute_b32 v15, v9, v8
	v_cndmask_b32_e64 v0, v4, v0, s[46:47]
	ds_bpermute_b32 v4, v9, v0
	v_cmp_gt_u32_e64 s[46:47], 8, v11
	s_waitcnt lgkmcnt(1)
	v_add_f32_e32 v9, v8, v15
	v_cndmask_b32_e64 v8, v9, v8, s[46:47]
	ds_bpermute_b32 v9, v13, v8
	s_waitcnt lgkmcnt(1)
	v_add_f32_e32 v4, v0, v4
	v_cndmask_b32_e64 v0, v4, v0, s[46:47]
	ds_bpermute_b32 v4, v13, v0
	v_cmp_gt_u32_e64 s[46:47], 16, v11
	s_waitcnt lgkmcnt(1)
	v_add_f32_e32 v9, v8, v9
	v_lshlrev_b32_e32 v13, 2, v14
	v_cndmask_b32_e64 v8, v9, v8, s[46:47]
	ds_bpermute_b32 v9, v13, v8
	s_waitcnt lgkmcnt(1)
	v_add_f32_e32 v4, v0, v4
	v_cndmask_b32_e64 v0, v4, v0, s[46:47]
	ds_bpermute_b32 v4, v13, v0
	v_lshl_or_b32 v13, v208, 2, v222
	s_waitcnt lgkmcnt(1)
	v_add_f32_e32 v9, v8, v9
	v_cndmask_b32_e32 v8, v9, v8, vcc
	v_add_f32_e32 v9, 0, v8
	ds_bpermute_b32 v8, v13, v8
	s_waitcnt lgkmcnt(1)
	v_add_f32_e32 v4, v0, v4
	v_cndmask_b32_e32 v15, v4, v0, vcc
	ds_bpermute_b32 v0, v13, v15
	v_lshl_add_u32 v14, v11, 2, s82
	v_sub_f32_e32 v4, v9, v6
	ds_write_b32 v14, v4
	s_waitcnt lgkmcnt(2)
	v_add_f32_e32 v4, 0, v8
	v_lshl_add_u32 v6, v7, 2, s82
	v_add_f32_e32 v7, v4, v15
	v_sub_f32_e32 v5, v7, v5
	ds_write_b32 v6, v5
	s_and_saveexec_b64 s[0:1], s[44:45]
	s_cbranch_execz .LBB0_452
	s_mul_i32 s23, s24, 0x408
	s_or_b32 s23, s23, s41
	s_add_i32 s34, s23, 0x400
	s_lshl_b64 s[44:45], s[34:35], 2
	s_add_u32 s44, s52, s44
	s_addc_u32 s45, s53, s45
	s_waitcnt lgkmcnt(2)
	v_add_f32_e32 v0, v4, v0
	v_readlane_b32 s23, v255, 10
	s_waitcnt vmcnt(0)
	v_mov_b32_e32 v4, v124
	v_add_f32_e32 v5, v0, v4
	v_sub_f32_e32 v4, v5, v4
	v_mov_b32_e32 v0, s23
	ds_write_b64 v0, v[4:5]

; template <bool DIFF>
; __device__ __forceinline__ void attn_unit(const AttnP& A, int b, int h, int qi, ldsp lds) {
;     ...
;         const float q2 = __uint_as_float(A.nrm[(h) * 2]) + __uint_as_float(A.nrm[(h) * 2 + 1]), k2r = __uint_as_float(A.nrm[(8 + h) * 2]) + __uint_as_float(A.nrm[(8 + h) * 2 + 1]),
;                     k2m = (__uint_as_float(A.nrm[32 + h * 4]) + __uint_as_float(A.nrm[32 + h * 4 + 1])) + (__uint_as_float(A.nrm[32 + h * 4 + 2]) + __uint_as_float(A.nrm[32 + h * 4 + 3])), k2 = fmaxf(k2r, k2m);
;         const float thr = 2.0f * 1.03f * sqrtf(q2 * k2) + 40.0f;
;         if (tid < nt) { if (pref[qstart >> 6] - pref[tid + 1] >= -thr) atomicMin((int*)kst, tid); }
.LBB0_453:
	v_cmp_ge_i32_e32 vcc, s91, v148
	s_waitcnt lgkmcnt(0)
	s_barrier
	s_and_saveexec_b64 s[0:1], vcc
	s_cbranch_execz .LBB0_459
	s_lshl_b32 s23, s41, 3
	v_mov_b32_e32 v0, s23
	s_lshl_b32 s23, s41, 4
	s_waitcnt vmcnt(0)
	v_mov_b32_e32 v8, v116
	v_mov_b32_e32 v9, v117
	v_mov_b32_e32 v14, v118
	v_mov_b32_e32 v15, v119
	v_mov_b32_e32 v0, s23
	v_mov_b32_e32 v4, v120
	v_mov_b32_e32 v5, v121
	v_mov_b32_e32 v6, v122
	v_mov_b32_e32 v7, v123
	s_mov_b32 s23, 0xf800000
	s_lshr_b32 s22, s22, 4
	s_add_i32 s22, s82, s22
	v_lshl_add_u32 v0, v148, 2, s82
	s_waitcnt vmcnt(2)
	v_add_f32_e32 v13, v8, v9
	s_waitcnt vmcnt(1)
	v_add_f32_e32 v14, v14, v15
	s_waitcnt vmcnt(0)
	v_mov_b32_e32 v8, v5
	v_mov_b32_e32 v9, v6
	v_mov_b32_e32 v5, v7
	v_pk_add_f32 v[4:5], v[8:9], v[4:5]
	v_mov_b32_e32 v6, s22
	v_add_f32_e32 v4, v4, v5
	v_max_f32_e32 v4, v14, v4
	v_mul_f32_e32 v4, v13, v4
	v_mul_f32_e32 v5, 0x4f800000, v4
	v_cmp_gt_f32_e32 vcc, s23, v4
	ds_read_b32 v6, v6
	ds_read_b32 v0, v0 offset:4
	v_cndmask_b32_e32 v4, v4, v5, vcc
	v_sqrt_f32_e32 v5, v4
	s_waitcnt lgkmcnt(0)
	v_sub_f32_e32 v0, v6, v0
	v_add_u32_e32 v7, -1, v5
	v_add_u32_e32 v8, 1, v5
	v_fma_f32 v9, -v7, v5, v4
	v_fma_f32 v13, -v8, v5, v4
	v_cmp_ge_f32_e64 s[44:45], 0, v9
	s_nop 1
	v_cndmask_b32_e64 v5, v5, v7, s[44:45]
	v_cmp_lt_f32_e64 s[44:45], 0, v13
	s_nop 1
	v_cndmask_b32_e64 v5, v5, v8, s[44:45]
	v_mul_f32_e32 v7, 0x37800000, v5
	v_cndmask_b32_e32 v5, v5, v7, vcc
	v_cmp_class_f32_e32 vcc, v4, v206
	s_nop 1
	v_cndmask_b32_e32 v4, v5, v4, vcc
	v_fmamk_f32 v4, v4, 0x4003d70a, v207
	v_cmp_ge_f32_e64 s[22:23], v0, -v4
	s_and_b64 exec, exec, s[22:23]
	s_cbranch_execz .LBB0_459
	s_mov_b64 s[22:23], exec
	s_brev_b32 s34, -2

; template <bool DIFF>
; __device__ __forceinline__ void attn_unit(const AttnP& A, int b, int h, int qi, ldsp lds) {
;     ...
;         kt0 = *kst;
;     }
;     LOAD_TILE(kt0);
;     STORE_TILE(kt0 & 1);
;     __syncthreads();
;     float cq = 0.f;
;     if (!DIFF) cq = pref[q_pp >> 6] + A.cumloc[(Rb + q_pp) * 8 + h];
;     float mhat = 0.f, l_run = 0.f;
;     f32x16 negm;
; #pragma unroll
;     for (int r = 0; r < 16; ++r) negm[r] = 0.f;
;     f32x16 o[NTD];
; #pragma unroll
;     for (int t = 0; t < NTD; ++t)
; #pragma unroll
;         for (int r = 0; r < 16; ++r) o[t][r] = 0.f;
;     const int trb = (4 * hi + ((lane & 15) >> 2)) * VP + ((lane >> 4) & 1) * 32 + (lane & 3) * 8;
.LBB0_463:
	s_or_b64 exec, exec, s[0:1]
	s_cmp_gt_i32 s93, s91
	v_lshlrev_b32_e32 v151, 2, v12
	s_waitcnt lgkmcnt(0)
	s_barrier
	s_cbranch_scc1 .LBB0_486
	s_ashr_i32 s0, s40, 6
	s_lshl_b32 s0, s0, 2
	s_add_i32 s0, s82, s0
	v_lshlrev_b64 v[2:3], 5, v[2:3]
	v_mov_b32_e32 v6, s0
	v_lshl_add_u64 v[2:3], s[54:55], 0, v[2:3]
	s_lshl_b32 s0, s41, 2
	s_mov_b32 s1, s35
	v_lshl_add_u64 v[2:3], v[2:3], 0, s[0:1]
	ds_read_b32 v6, v6
	s_add_i32 s1, s91, -3
	s_and_b64 s[46:47], s[16:17], exec
	s_cselect_b32 s95, s1, 0
	s_or_b32 s96, s40, 31
	s_add_u32 s72, s54, s0
	s_addc_u32 s73, s55, 0
	s_lshl_b32 s0, s93, 2
	v_mov_b32_e32 v165, 0
	v_and_b32_e32 v163, 24, v7
	s_mov_b32 s94, 0
	v_mul_u32_u24_e32 v164, 0x90, v10
	v_cmp_gt_u32_e64 s[46:47], 32, v11
	v_lshl_add_u64 v[152:153], s[58:59], 0, v[4:5]
	s_add_i32 s97, s82, s0
	s_lshl_b32 s98, s93, 6
	v_mov_b32_e32 v154, 0
	v_mov_b32_e32 v34, 0
	v_mov_b32_e32 v35, v165
	v_mov_b32_e32 v36, v165
	v_mov_b32_e32 v37, v165
	v_mov_b32_e32 v38, v165
	v_mov_b32_e32 v39, v165
	v_mov_b32_e32 v40, v165
	v_mov_b32_e32 v41, v165
	v_mov_b32_e32 v42, v165
	v_mov_b32_e32 v43, v165
	v_mov_b32_e32 v44, v165
	v_mov_b32_e32 v45, v165
	v_mov_b32_e32 v46, v165
	v_mov_b32_e32 v47, v165
	v_mov_b32_e32 v48, v165
	v_mov_b32_e32 v49, v165
	v_mov_b32_e32 v18, 0
	v_mov_b32_e32 v19, v165
	v_mov_b32_e32 v20, v165
	v_mov_b32_e32 v21, v165
	v_mov_b32_e32 v22, v165
	v_mov_b32_e32 v23, v165
	v_mov_b32_e32 v24, v165
	v_mov_b32_e32 v25, v165
	v_mov_b32_e32 v26, v165
	v_mov_b32_e32 v27, v165
	v_mov_b32_e32 v28, v165
	v_mov_b32_e32 v29, v165
	v_mov_b32_e32 v30, v165
	v_mov_b32_e32 v31, v165
	v_mov_b32_e32 v32, v165
	v_mov_b32_e32 v33, v165
	v_mov_b32_e32 v3, v165
	v_mov_b32_e32 v4, v165
	v_mov_b32_e32 v5, v165
	v_mov_b32_e32 v7, v165
	v_mov_b32_e32 v8, v165
	v_mov_b32_e32 v9, v165
	v_mov_b32_e32 v10, v165
	v_mov_b32_e32 v11, v165
	v_mov_b32_e32 v12, v165
	v_mov_b32_e32 v13, v165
	v_mov_b32_e32 v14, v165
	v_mov_b32_e32 v15, v165
	v_mov_b32_e32 v16, v165
	v_mov_b32_e32 v17, v165
	s_waitcnt vmcnt(0) lgkmcnt(0)
	v_mov_b32_e32 v2, v125
	v_add_f32_e32 v160, v6, v2
	v_lshrrev_b32_e32 v2, 2, v148
	v_and_or_b32 v2, v2, 3, v151
	v_mul_u32_u24_e32 v161, 0xc0, v2
	v_lshlrev_b32_e32 v2, 1, v148
	v_and_b32_e32 v162, 32, v2
	v_mov_b32_e32 v2, v165
	v_mov_b32_e32 v6, v165
	s_lshr_b32 s64, s96, 6
	s_add_i32 s64, s64, 1
	s_add_i32 s0, s91, 1
	s_min_i32 s64, s64, s0
	v_add_u32_e32 v156, v156, v157
	v_add_u32_e32 v158, v158, v157
	v_add3_u32 v161, v161, v162, v163
	v_add_u32_e32 v150, v164, v150
	s_lshl_b64 s[40:41], s[22:23], 13
	v_lshl_add_u64 v[152:153], v[152:153], 0, s[40:41]
	v_lshl_add_u64 v[152:153], v[152:153], 0, v[0:1]
	s_mov_b32 s65, s35
	s_lshl_b32 s0, s93, 19
	s_mov_b32 s1, s35
	s_lshr_b32 s1, s93, 13
	v_lshl_add_u64 v[152:153], v[152:153], 0, s[0:1]
	s_or_b32 s0, s92, 0xc00
	s_lshl_b32 s0, s0, 1
	s_mov_b32 s1, s35
	v_lshl_add_u64 v[250:251], v[152:153], 0, s[0:1]
	v_lshl_add_u64 v[250:251], v[250:251], 0, s[26:27]
	v_lshl_add_u64 v[152:153], v[152:153], 0, s[34:35]
	v_lshl_add_u64 v[152:153], v[152:153], 0, s[26:27]
	s_add_i32 s0, s93, 1
	s_lshl_b32 s0, s0, 6
	s_mov_b32 s1, s35
	s_add_u32 s0, s0, s22
	s_addc_u32 s1, s1, s23
	v_lshl_add_u64 v[252:253], s[0:1], 0, v[148:149]
	v_lshlrev_b64 v[252:253], 5, v[252:253]
	v_lshl_add_u64 v[252:253], s[72:73], 0, v[252:253]
	s_cmp_ge_i32 s93, s91
	s_cbranch_scc1 .Lfx_noinit
	global_load_dwordx4 v[98:101], v[152:153], off
	v_lshl_add_u64 v[152:153], v[152:153], 0, s[26:27]
	s_and_saveexec_b64 s[0:1], s[44:45]
	global_load_dword v155, v[252:253], off
	s_mov_b64 exec, s[0:1]
	s_mov_b64 s[0:1], 0x800
	v_lshl_add_u64 v[252:253], v[252:253], 0, s[0:1]
